# norm phases: adaLN table fill issues all 14 loads then one wait; P17 and P6/P9 bf16 row loops software-pipelined by one row (next row loaded before this row's stores)
# speedup vs baseline: 1.0104x; 1.0003x over previous
;     ...
;     for (int i = F.tid; i < 1024; i += NWAVES * 64) {
;         gl[i] = gw_[i];
; #pragma unroll
;         for (int cnd = 0; cnd < 3; ++cnd) {
;             float sh, sc;
;             if (from_partials) { sh = ada_b[layer * 6144 + offsh + i]; sc = ada_b[layer * 6144 + offsc + i];
;                 float ph[ADA_KS], pc[ADA_KS];
; #pragma unroll
;                 for (int ks = 0; ks < ADA_KS; ++ks) { const float* p = modp + ((size_t)(ks * 2 + layer) * 3 + cnd) * 6144; ph[ks] = p[offsh + i]; pc[ks] = p[offsc + i]; }
; #pragma unroll
;                 for (int ks = 0; ks < ADA_KS; ++ks) { sh += ph[ks]; sc += pc[ks]; } }
;             else { sh = mod[(layer * 3 + cnd) * 6144 + offsh + i]; sc = mod[(layer * 3 + cnd) * 6144 + offsc + i]; }
;             scl[cnd * 1024 + i] = 1.f + sc; shl[cnd * 1024 + i] = sh;
;         }
;     }
.LBB0_40:
	v_lshlrev_b32_e32 v220, 2, v2
	v_lshlrev_b32_e32 v221, 2, v3
	global_load_dword v236, v220, s[4:5]
	global_load_dword v237, v221, s[4:5]
	v_add_u32_e32 v222, s12, v220
	v_add_u32_e32 v223, s12, v221
	global_load_dword v228, v222, s[8:9] offset:-4096
	global_load_dword v229, v223, s[8:9] offset:-4096
	global_load_dword v230, v222, s[8:9]
	global_load_dword v231, v223, s[8:9]
	v_add_u32_e32 v222, s13, v220
	v_add_u32_e32 v223, s13, v221
	global_load_dword v232, v222, s[8:9] offset:-4096
	global_load_dword v233, v223, s[8:9] offset:-4096
	global_load_dword v234, v222, s[8:9]
	global_load_dword v235, v223, s[8:9]
	v_add_u32_e32 v222, s14, v220
	v_add_u32_e32 v223, s14, v221
	global_load_dword v238, v222, s[8:9] offset:-4096
	global_load_dword v239, v223, s[8:9] offset:-4096
	global_load_dword v240, v222, s[8:9]
	global_load_dword v241, v223, s[8:9]
	v_add_u32_e32 v5, -2, v5
	v_add_u32_e32 v224, 0x400, v2
	v_add_u32_e32 v225, 0x400, v3
	v_lshl_add_u32 v226, v224, 2, 0
	v_lshl_add_u32 v227, v225, 2, 0
	v_cmp_eq_u32_e32 vcc, 0, v5
	s_or_b64 s[10:11], vcc, s[10:11]
	s_waitcnt vmcnt(0)
	ds_write2st64_b32 v6, v236, v237 offset1:8
	v_add_f32_e32 v230, 1.0, v230
	v_add_f32_e32 v231, 1.0, v231
	ds_write2st64_b32 v6, v230, v231 offset0:16 offset1:24
	ds_write2st64_b32 v6, v228, v229 offset0:64 offset1:72
	v_add_f32_e32 v234, 1.0, v234
	v_add_f32_e32 v235, 1.0, v235
	ds_write_b32 v226, v234 offset:4096
	ds_write_b32 v227, v235 offset:4096
	ds_write_b32 v226, v232 offset:16384
	ds_write_b32 v227, v233 offset:16384
	v_add_f32_e32 v240, 1.0, v240
	v_add_f32_e32 v241, 1.0, v241
	ds_write_b32 v220, v240 offset:12288
	ds_write_b32 v221, v241 offset:12288
	ds_write_b32 v220, v238 offset:24576
	ds_write_b32 v221, v239 offset:24576
	v_add_u32_e32 v6, 0x1000, v6
	v_mov_b32_e32 v2, v224
	v_mov_b32_e32 v3, v225
	s_andn2_b64 exec, exec, s[10:11]
	s_cbranch_execnz .LBB0_40
	s_nop 0
	s_nop 0
	s_nop 0
	s_nop 0
	s_nop 0
	s_nop 0
	s_nop 0
	s_nop 0
	s_nop 0
	s_nop 0
	s_nop 0
	s_nop 0
	s_nop 0
	s_nop 0
	s_nop 0
	s_nop 0
	s_nop 0
	s_nop 0
	s_nop 0
	s_nop 0
	s_nop 0
	s_nop 0
	s_nop 0
	s_nop 0
	s_nop 0
	s_nop 0
	s_or_b64 exec, exec, s[10:11]
	v_cmp_ne_u32_e32 vcc, v0, v4
	v_lshl_add_u32 v2, v4, 9, v170
	s_orn2_b64 s[8:9], vcc, exec

; #define GAS __attribute__((address_space(1)))
;     ...
;     bf16* XN = (bf16*)(F.ws + WS_XN);
;     const int gw = F.vcu * NWAVES + F.wave, NGW = F.G * NWAVES;
;     for (int m = gw; m < nrows; m += NGW) {
;         const float* xrow = m < ML ? src_lat + (size_t)m * DM : src_ctx + (size_t)(m - ML) * DM;
;         const int cnd = m < SEQ ? 0 : (m < ML ? 1 : 2);
;         const GAS f32x4* xr = (const GAS f32x4*)xrow + F.lane;
;         f32x4 v[4]; float s = 0.f;
;         if (lat_bf16 && m < ML) {
;             const GAS v2u* xb = (const GAS v2u*)((const bf16*)src_lat + (size_t)m * DM) + F.lane;
;             v2u w[4];
; #pragma unroll
;             for (int j = 0; j < 4; ++j) w[j] = xb[64 * j];
; #pragma unroll
;             for (int j = 0; j < 4; ++j) v[j] = f32x4{bflo(w[j].x), bfhi(w[j].x), bflo(w[j].y), bfhi(w[j].y)};
.LBB0_45:
	s_or_b64 exec, exec, s[2:3]
	v_readlane_b32 s2, v243, 20
	s_lshl_b32 s2, s2, 3
	v_readlane_b32 s3, v243, 24
	s_add_i32 s2, s2, s3
	s_cmpk_gt_i32 s2, 0x3fff
	s_waitcnt lgkmcnt(0)
	s_barrier
	s_cbranch_scc1 .LBB0_48
	v_lshl_add_u32 v46, v172, 4, 0
	v_readlane_b32 s3, v243, 18
	s_waitcnt vmcnt(0)
	ds_read_b128 v[2:5], v46
	ds_read_b128 v[6:9], v46 offset:1024
	ds_read_b128 v[10:13], v46 offset:2048
	ds_read_b128 v[14:17], v46 offset:3072
	s_lshl_b32 s6, s3, 3
	s_ashr_i32 s3, s2, 31
	s_lshl_b64 s[4:5], s[2:3], 11
	s_add_u32 s4, s80, s4
	v_lshlrev_b32_e32 v0, 3, v172
	s_addc_u32 s5, s81, s5
	v_lshl_add_u64 v[18:19], s[4:5], 0, v[0:1]
	s_mov_b64 s[4:5], 0xd900000
	s_ashr_i32 s7, s6, 31
	v_lshl_add_u64 v[26:27], v[18:19], 0, s[4:5]
	s_lshl_b64 s[8:9], s[6:7], 11
	s_mov_b32 s11, 0xffff0000
	s_mov_b32 s12, 0xf800000
	s_movk_i32 s13, 0x7fff
	global_load_dwordx2 v[18:19], v[26:27], off
	global_load_dwordx2 v[20:21], v[26:27], off offset:512
	global_load_dwordx2 v[22:23], v[26:27], off offset:1024
	global_load_dwordx2 v[24:25], v[26:27], off offset:1536
	s_waitcnt vmcnt(0)
	s_branch .Lp17_body

; #define GAS __attribute__((address_space(1)))
;     ...
;     for (int m = gw; m < nrows; m += NGW) {
;         const float* xrow = m < ML ? src_lat + (size_t)m * DM : src_ctx + (size_t)(m - ML) * DM;
;         const int cnd = m < SEQ ? 0 : (m < ML ? 1 : 2);
;         const GAS f32x4* xr = (const GAS f32x4*)xrow + F.lane;
;         f32x4 v[4]; float s = 0.f;
;         if (lat_bf16 && m < ML) {
;             const GAS v2u* xb = (const GAS v2u*)((const bf16*)src_lat + (size_t)m * DM) + F.lane;
;             v2u w[4];
; #pragma unroll
;             for (int j = 0; j < 4; ++j) w[j] = xb[64 * j];
; #pragma unroll
;             for (int j = 0; j < 4; ++j) v[j] = f32x4{bflo(w[j].x), bfhi(w[j].x), bflo(w[j].y), bfhi(w[j].y)};
;         } else {
; #pragma unroll
;             for (int j = 0; j < 4; ++j) v[j] = xr[64 * j];
;         }
;         if (nparts > 0 && m >= ML) {
;             for (int p = 0; p < nparts; p += 4) {
;                 const GAS f32x4* pr = (const GAS f32x4*)(parts + (size_t)p * (512 * 1024) + (size_t)(m - ML) * DM) + F.lane;
;                 f32x4 w[4][4];
; #pragma unroll
;                 for (int q = 0; q < 4; ++q)
; #pragma unroll
;                     for (int j = 0; j < 4; ++j) w[q][j] = pr[(size_t)q * (512 * 1024 / 4) + 64 * j];
; #pragma unroll
;                 for (int j = 0; j < 4; ++j) v[j] += (w[0][j] + w[1][j]) + (w[2][j] + w[3][j]); }
;             GAS f32x4* cr = (GAS f32x4*)((float*)(F.ws + WS_CTXRES) + (size_t)(m - ML) * DM) + F.lane;
; #pragma unroll
;             for (int j = 0; j < 4; ++j) cr[64 * j] = v[j];
;         }
; #pragma unroll
;         for (int j = 0; j < 4; ++j) s += (v[j].x * v[j].x + v[j].y * v[j].y) + (v[j].z * v[j].z + v[j].w * v[j].w);
;         const float rstd = 1.f / sqrtf(wave_sum(s, F.lane) * (1.f / DM) + NORM_EPS);
.Lp17_body:
	s_cmpk_lt_i32 s2, 0x2000
	s_cselect_b32 s3, 0, 0x1000
	s_add_i32 s2, s2, s6
	s_cmpk_lt_i32 s2, 0x4000
	v_mov_b64_e32 v[220:221], v[18:19]
	v_mov_b64_e32 v[222:223], v[20:21]
	v_mov_b64_e32 v[224:225], v[22:23]
	v_mov_b64_e32 v[226:227], v[24:25]
	v_mov_b64_e32 v[228:229], v[26:27]
	v_lshl_add_u64 v[26:27], v[26:27], 0, s[8:9]
	s_cbranch_scc0 .Lp17_nopf
	global_load_dwordx2 v[18:19], v[26:27], off
	global_load_dwordx2 v[20:21], v[26:27], off offset:512
	global_load_dwordx2 v[22:23], v[26:27], off offset:1024
	global_load_dwordx2 v[24:25], v[26:27], off offset:1536
.Lp17_nopf:
	v_and_b32_e32 v45, 0xffff0000, v221
	v_and_b32_e32 v43, 0xffff0000, v220
	v_lshlrev_b32_e32 v44, 16, v221
	v_mul_f32_e32 v0, v45, v45
	v_lshlrev_b32_e32 v42, 16, v220
	v_pk_fma_f32 v[220:221], v[44:45], v[44:45], v[0:1] op_sel_hi:[1,1,0]
	v_and_b32_e32 v41, 0xffff0000, v223
	v_and_b32_e32 v40, 0xffff0000, v222
	v_mul_f32_e32 v0, v43, v43
	v_lshlrev_b32_e32 v31, 16, v226
	v_lshlrev_b32_e32 v39, 16, v223
	v_lshlrev_b32_e32 v38, 16, v222
	v_pk_mul_f32 v[222:223], v[40:41], v[40:41]
	v_lshlrev_b32_e32 v34, 16, v224
	v_and_b32_e32 v35, 0xffff0000, v224
	v_lshlrev_b32_e32 v36, 16, v225
	v_and_b32_e32 v37, 0xffff0000, v225
	v_pk_fma_f32 v[224:225], v[42:43], v[42:43], v[0:1] op_sel_hi:[1,1,0]
	v_and_b32_e32 v29, 0xffff0000, v226
	v_lshlrev_b32_e32 v32, 16, v227
	v_and_b32_e32 v33, 0xffff0000, v227
	v_pk_fma_f32 v[222:223], v[38:39], v[38:39], v[222:223]
	v_mov_b32_e32 v30, v224
	v_mov_b32_e32 v226, v220
	v_mov_b32_e32 v227, v31
	v_mul_f32_e32 v28, v29, v29
	v_pk_add_f32 v[220:221], v[224:225], v[220:221]
	v_pk_mul_f32 v[224:225], v[30:31], v[226:227]
	v_pk_add_f32 v[222:223], v[222:223], v[222:223] op_sel:[0,1] op_sel_hi:[1,0]
	v_mov_b32_e32 v221, v225
	v_mov_b32_e32 v223, v28
	v_mul_f32_e32 v0, v35, v35
	v_pk_add_f32 v[220:221], v[220:221], v[222:223]
	v_pk_fma_f32 v[222:223], v[34:35], v[34:35], v[0:1] op_sel_hi:[1,1,0]
	v_mul_f32_e32 v0, v37, v37
	v_mul_f32_e32 v47, v32, v32
	v_mul_f32_e32 v48, v33, v33
	v_pk_fma_f32 v[224:225], v[36:37], v[36:37], v[0:1] op_sel_hi:[1,1,0]
	v_mov_b32_e32 v223, v47
	v_mov_b32_e32 v225, v48
	v_pk_add_f32 v[222:223], v[222:223], v[224:225]
	v_add_u32_e32 v28, s3, v46
	v_pk_add_f32 v[220:221], v[220:221], v[222:223]
	s_mov_b32 s3, 0xf5a00000
	v_add_f32_e32 v0, v220, v221
	s_nop 1
	v_add_f32_dpp v0, v0, v0 row_ror:8 row_mask:0xf bank_mask:0xf bound_ctrl:1
	s_nop 1
	v_add_f32_dpp v0, v0, v0 row_ror:4 row_mask:0xf bank_mask:0xf bound_ctrl:1
	s_nop 1
	v_add_f32_dpp v0, v0, v0 row_ror:2 row_mask:0xf bank_mask:0xf bound_ctrl:1
	s_nop 1
	v_add_f32_dpp v0, v0, v0 row_ror:1 row_mask:0xf bank_mask:0xf bound_ctrl:1
	s_nop 0
	v_readlane_b32 s7, v0, 16
	v_readlane_b32 s10, v0, 48
	v_readlane_b32 s4, v0, 0
	v_readlane_b32 s5, v0, 32
	v_mov_b32_e32 v220, s7
	v_mov_b32_e32 v221, s10
	v_pk_add_f32 v[220:221], s[4:5], v[220:221]
	s_nop 0
	v_add_f32_e32 v0, v220, v221
	v_fmamk_f32 v0, v0, 0x3a800000, v173
	v_cmp_gt_f32_e32 vcc, s12, v0
	v_mul_f32_e32 v220, 0x4f800000, v0
	s_nop 0
	v_cndmask_b32_e32 v0, v0, v220, vcc
	v_sqrt_f32_e32 v220, v0
	s_nop 0
	v_add_u32_e32 v221, -1, v220
	v_fma_f32 v222, -v221, v220, v0
	v_cmp_ge_f32_e64 s[4:5], 0, v222
	v_add_u32_e32 v222, 1, v220
	s_nop 0
	v_cndmask_b32_e64 v221, v220, v221, s[4:5]
	v_fma_f32 v220, -v222, v220, v0
	v_cmp_lt_f32_e64 s[4:5], 0, v220
	s_nop 1
	v_cndmask_b32_e64 v220, v221, v222, s[4:5]
	v_mul_f32_e32 v221, 0x37800000, v220
	v_cndmask_b32_e32 v220, v220, v221, vcc
	v_cmp_class_f32_e32 vcc, v0, v186
	s_nop 1
	v_cndmask_b32_e32 v0, v220, v0, vcc
	v_div_scale_f32 v220, s[4:5], v0, v0, 1.0
	v_rcp_f32_e32 v221, v220
	s_nop 0
	v_fma_f32 v222, -v220, v221, 1.0
	v_fmac_f32_e32 v221, v222, v221
	v_div_scale_f32 v222, vcc, 1.0, v0, 1.0
	v_mul_f32_e32 v223, v222, v221
	v_fma_f32 v224, -v220, v223, v222
	v_fmac_f32_e32 v223, v224, v221
	v_fma_f32 v220, -v220, v223, v222
	v_div_fmas_f32 v220, v220, v221, v223
	v_div_fixup_f32 v0, v220, v0, 1.0
	ds_read_b128 v[220:223], v28 offset:4096
	ds_read_b128 v[224:227], v28 offset:16384
	v_pk_mul_f32 v[42:43], v[42:43], v[0:1] op_sel_hi:[1,0]
	v_pk_mul_f32 v[44:45], v[44:45], v[0:1] op_sel_hi:[1,0]
	s_waitcnt lgkmcnt(5)
; #define GAS __attribute__((address_space(1)))
; #define LAS __attribute__((address_space(3)))
; __device__ __forceinline__ unsigned pk2(float lo, float hi) { return f2bf(lo) | (f2bf(hi) << 16); }
; __device__ __forceinline__ unsigned pk4f8(float a, float b, float c, float d) { int w = 0; w = __builtin_amdgcn_cvt_pk_fp8_f32(a, b, w, false); w = __builtin_amdgcn_cvt_pk_fp8_f32(c, d, w, true); return (unsigned)w; }
;     ...
;         GAS v2u* o8 = (GAS v2u*)(XN + (size_t)m * DM) + F.lane;
;         GAS unsigned* o4 = (GAS unsigned*)((unsigned char*)XN + (size_t)m * DM) + F.lane;
; #pragma unroll
;         for (int j = 0; j < 4; ++j) { const int col = 4 * F.lane + 256 * j;
;             const f32x4 g = *(const LAS f32x4*)(gl + col), sc = *(const LAS f32x4*)(scl + cnd * 1024 + col), sh = *(const LAS f32x4*)(shl + cnd * 1024 + col);
;             const f32x4 y = (v[j] * rstd) * g * sc + sh;
;             if (xn_fp8) o4[64 * j] = pk4f8(y.x, y.y, y.z, y.w);
;             else { v2u w; w.x = pk2(y.x, y.y); w.y = pk2(y.z, y.w); o8[64 * j] = w; } }
	v_pk_mul_f32 v[42:43], v[2:3], v[42:43]
	v_pk_mul_f32 v[44:45], v[4:5], v[44:45]
	s_waitcnt lgkmcnt(0)
	v_pk_fma_f32 v[220:221], v[220:221], v[42:43], v[224:225]
	v_pk_fma_f32 v[222:223], v[222:223], v[44:45], v[226:227]
	v_bfe_u32 v224, v220, 16, 1
	v_add3_u32 v220, v220, v224, s13
	v_bfe_u32 v224, v221, 16, 1
	v_lshrrev_b32_e32 v220, 16, v220
	v_add3_u32 v221, v221, v224, s13
	v_and_or_b32 v220, v221, s11, v220
	v_bfe_u32 v221, v222, 16, 1
	v_add3_u32 v221, v222, v221, s13
	v_bfe_u32 v222, v223, 16, 1
	v_lshrrev_b32_e32 v221, 16, v221
	v_add3_u32 v222, v223, v222, s13
	v_and_or_b32 v221, v222, s11, v221
	v_add_co_u32_e32 v222, vcc, s3, v228
	v_mov_b32_e32 v42, v39
	s_nop 0
	v_addc_co_u32_e32 v223, vcc, -1, v229, vcc
	global_store_dwordx2 v[222:223], v[220:221], off
	ds_read_b128 v[220:223], v28 offset:5120
	ds_read_b128 v[224:227], v28 offset:17408
	v_mov_b32_e32 v39, v40
	v_pk_mul_f32 v[38:39], v[38:39], v[0:1] op_sel_hi:[1,0]
	v_mov_b32_e32 v43, v41
	v_pk_mul_f32 v[38:39], v[6:7], v[38:39]
	v_pk_mul_f32 v[42:43], v[42:43], v[0:1] op_sel_hi:[1,0]
	s_waitcnt lgkmcnt(0)
	v_pk_fma_f32 v[220:221], v[220:221], v[38:39], v[224:225]
	v_pk_mul_f32 v[40:41], v[8:9], v[42:43]
	v_bfe_u32 v224, v220, 16, 1
	v_add3_u32 v220, v220, v224, s13
	v_bfe_u32 v224, v221, 16, 1
	v_pk_fma_f32 v[222:223], v[222:223], v[40:41], v[226:227]
	v_lshrrev_b32_e32 v220, 16, v220
	v_add3_u32 v221, v221, v224, s13
	v_and_or_b32 v220, v221, s11, v220
	v_bfe_u32 v221, v222, 16, 1
	v_add3_u32 v221, v222, v221, s13
	v_bfe_u32 v222, v223, 16, 1
	s_mov_b32 s3, 0xf5a01000
	v_lshrrev_b32_e32 v221, 16, v221
	v_add3_u32 v222, v223, v222, s13
	v_add_co_u32_e32 v38, vcc, s3, v228
	v_and_or_b32 v221, v222, s11, v221
	s_nop 0
	v_addc_co_u32_e32 v39, vcc, -1, v229, vcc
	global_store_dwordx2 v[38:39], v[220:221], off offset:-3584
	ds_read_b128 v[220:223], v28 offset:6144
	ds_read_b128 v[224:227], v28 offset:18432
	v_pk_mul_f32 v[34:35], v[34:35], v[0:1] op_sel_hi:[1,0]
	v_pk_mul_f32 v[36:37], v[36:37], v[0:1] op_sel_hi:[1,0]
	v_pk_mul_f32 v[34:35], v[10:11], v[34:35]
	v_pk_mul_f32 v[36:37], v[12:13], v[36:37]
	s_waitcnt lgkmcnt(0)
	v_pk_fma_f32 v[220:221], v[220:221], v[34:35], v[224:225]
	v_pk_fma_f32 v[222:223], v[222:223], v[36:37], v[226:227]
	v_bfe_u32 v224, v220, 16, 1
	v_add3_u32 v220, v220, v224, s13
	v_bfe_u32 v224, v221, 16, 1
	v_lshrrev_b32_e32 v220, 16, v220
	v_add3_u32 v221, v221, v224, s13
	v_and_or_b32 v220, v221, s11, v220
	v_bfe_u32 v221, v222, 16, 1
	v_add3_u32 v221, v222, v221, s13
	v_bfe_u32 v222, v223, 16, 1
	v_lshrrev_b32_e32 v221, 16, v221
	v_add3_u32 v222, v223, v222, s13
	v_and_or_b32 v221, v222, s11, v221
	global_store_dwordx2 v[38:39], v[220:221], off offset:-3072
	ds_read_b128 v[220:223], v28 offset:7168
	ds_read_b128 v[224:227], v28 offset:19456
	v_mov_b32_e32 v28, v31
	v_pk_mul_f32 v[28:29], v[0:1], v[28:29] op_sel_hi:[0,1]
	v_pk_mul_f32 v[28:29], v[28:29], v[14:15]
	v_pk_mul_f32 v[32:33], v[0:1], v[32:33] op_sel_hi:[0,1]
	s_waitcnt lgkmcnt(0)
	v_pk_fma_f32 v[220:221], v[28:29], v[220:221], v[224:225]
	v_pk_mul_f32 v[30:31], v[32:33], v[16:17]
	v_bfe_u32 v0, v220, 16, 1
	v_add3_u32 v0, v220, v0, s13
	v_bfe_u32 v220, v221, 16, 1
	v_pk_fma_f32 v[222:223], v[30:31], v[222:223], v[226:227]
	v_lshrrev_b32_e32 v0, 16, v0
	v_add3_u32 v220, v221, v220, s13
	v_and_or_b32 v220, v220, s11, v0
	v_bfe_u32 v0, v222, 16, 1
	v_add3_u32 v0, v222, v0, s13
	v_bfe_u32 v221, v223, 16, 1
	v_lshrrev_b32_e32 v0, 16, v0
	v_add3_u32 v221, v223, v221, s13
	v_and_or_b32 v221, v221, s11, v0
	global_store_dwordx2 v[38:39], v[220:221], off offset:-2560
	s_cbranch_scc1 .LBB0_47

;     ...
;     for (int i = F.tid; i < 1024; i += NWAVES * 64) {
;         gl[i] = gw_[i];
; #pragma unroll
;         for (int cnd = 0; cnd < 3; ++cnd) {
;             float sh, sc;
;             if (from_partials) { sh = ada_b[layer * 6144 + offsh + i]; sc = ada_b[layer * 6144 + offsc + i];
;                 float ph[ADA_KS], pc[ADA_KS];
; #pragma unroll
;                 for (int ks = 0; ks < ADA_KS; ++ks) { const float* p = modp + ((size_t)(ks * 2 + layer) * 3 + cnd) * 6144; ph[ks] = p[offsh + i]; pc[ks] = p[offsc + i]; }
; #pragma unroll
;                 for (int ks = 0; ks < ADA_KS; ++ks) { sh += ph[ks]; sc += pc[ks]; } }
;             else { sh = mod[(layer * 3 + cnd) * 6144 + offsh + i]; sc = mod[(layer * 3 + cnd) * 6144 + offsc + i]; }
;             scl[cnd * 1024 + i] = 1.f + sc; shl[cnd * 1024 + i] = sh;
;         }
;     }
.LBB0_153:
	v_lshlrev_b32_e32 v220, 2, v2
	v_lshlrev_b32_e32 v221, 2, v3
	global_load_dword v236, v220, s[4:5]
	global_load_dword v237, v221, s[4:5]
	v_add_u32_e32 v222, s12, v220
	v_add_u32_e32 v223, s12, v221
	global_load_dword v228, v222, s[8:9] offset:-4096
	global_load_dword v229, v223, s[8:9] offset:-4096
	global_load_dword v230, v222, s[8:9]
	global_load_dword v231, v223, s[8:9]
	v_add_u32_e32 v222, s13, v220
	v_add_u32_e32 v223, s13, v221
	global_load_dword v232, v222, s[8:9] offset:-4096
	global_load_dword v233, v223, s[8:9] offset:-4096
	global_load_dword v234, v222, s[8:9]
	global_load_dword v235, v223, s[8:9]
	v_add_u32_e32 v222, s14, v220
	v_add_u32_e32 v223, s14, v221
	global_load_dword v238, v222, s[8:9] offset:-4096
	global_load_dword v239, v223, s[8:9] offset:-4096
	global_load_dword v240, v222, s[8:9]
	global_load_dword v241, v223, s[8:9]
	v_add_u32_e32 v7, -2, v7
	v_add_u32_e32 v224, 0x400, v2
	v_add_u32_e32 v225, 0x400, v3
	v_lshl_add_u32 v226, v224, 2, 0
	v_lshl_add_u32 v227, v225, 2, 0
	v_cmp_eq_u32_e32 vcc, 0, v7
	s_or_b64 s[10:11], vcc, s[10:11]
	s_waitcnt vmcnt(0)
	ds_write2st64_b32 v8, v236, v237 offset1:8
	v_add_f32_e32 v230, 1.0, v230
	v_add_f32_e32 v231, 1.0, v231
	ds_write2st64_b32 v8, v230, v231 offset0:16 offset1:24
	ds_write2st64_b32 v8, v228, v229 offset0:64 offset1:72
	v_add_f32_e32 v234, 1.0, v234
	v_add_f32_e32 v235, 1.0, v235
	ds_write_b32 v226, v234 offset:4096
	ds_write_b32 v227, v235 offset:4096
	ds_write_b32 v226, v232 offset:16384
	ds_write_b32 v227, v233 offset:16384
	v_add_f32_e32 v240, 1.0, v240
	v_add_f32_e32 v241, 1.0, v241
	ds_write_b32 v220, v240 offset:12288
	ds_write_b32 v221, v241 offset:12288
	ds_write_b32 v220, v238 offset:24576
	ds_write_b32 v221, v239 offset:24576
	v_add_u32_e32 v8, 0x1000, v8
	v_mov_b32_e32 v2, v224
	v_mov_b32_e32 v3, v225
	s_andn2_b64 exec, exec, s[10:11]
	s_cbranch_execnz .LBB0_153
	s_nop 0
	s_nop 0
	s_nop 0
	s_nop 0
	s_nop 0
	s_nop 0
	s_nop 0
	s_nop 0
	s_nop 0
	s_nop 0
	s_nop 0
	s_nop 0
	s_nop 0
	s_nop 0
	s_nop 0
	s_nop 0
	s_nop 0
	s_nop 0
	s_nop 0
	s_nop 0
	s_nop 0
	s_nop 0
	s_nop 0
	s_nop 0
	s_nop 0
	s_nop 0
	s_nop 0
	s_nop 0
	s_nop 0
	s_nop 0
	s_nop 0
	s_nop 0
	s_nop 0
	s_or_b64 exec, exec, s[10:11]
	v_cmp_ne_u32_e32 vcc, v0, v6
	v_lshl_add_u32 v2, v6, 9, v170
	s_orn2_b64 s[8:9], vcc, exec

; #define GAS __attribute__((address_space(1)))
;     ...
;     bf16* XN = (bf16*)(F.ws + WS_XN);
;     const int gw = F.vcu * NWAVES + F.wave, NGW = F.G * NWAVES;
;     for (int m = gw; m < nrows; m += NGW) {
;         const float* xrow = m < ML ? src_lat + (size_t)m * DM : src_ctx + (size_t)(m - ML) * DM;
;         const int cnd = m < SEQ ? 0 : (m < ML ? 1 : 2);
;         const GAS f32x4* xr = (const GAS f32x4*)xrow + F.lane;
;         f32x4 v[4]; float s = 0.f;
;         if (lat_bf16 && m < ML) {
;             const GAS v2u* xb = (const GAS v2u*)((const bf16*)src_lat + (size_t)m * DM) + F.lane;
;             v2u w[4];
; #pragma unroll
;             for (int j = 0; j < 4; ++j) w[j] = xb[64 * j];
; #pragma unroll
;             for (int j = 0; j < 4; ++j) v[j] = f32x4{bflo(w[j].x), bfhi(w[j].x), bflo(w[j].y), bfhi(w[j].y)};
.LBB0_158:
	s_or_b64 exec, exec, s[0:1]
	v_readlane_b32 s0, v243, 20
	s_lshl_b32 s0, s0, 3
	v_readlane_b32 s1, v243, 24
	s_add_i32 s0, s0, s1
	s_cmpk_gt_i32 s0, 0x41ff
	s_waitcnt lgkmcnt(0)
	s_barrier
	s_cbranch_scc1 .LBB0_178
	v_readlane_b32 s1, v243, 18
	s_lshl_b32 s6, s1, 3
	v_lshlrev_b32_e32 v0, 4, v172
	s_add_u32 s16, s80, 0xd900000
	s_waitcnt vmcnt(35)
	v_add_u32_e32 v102, 0, v0
	v_readlane_b32 s4, v243, 22
	s_addc_u32 s17, s81, 0
	s_waitcnt vmcnt(0)
	ds_read_b128 v[2:5], v102
	ds_read_b128 v[6:9], v102 offset:1024
	ds_read_b128 v[10:13], v102 offset:2048
	ds_read_b128 v[14:17], v102 offset:3072
	v_readlane_b32 s5, v243, 23
	s_ashr_i32 s1, s0, 31
	v_lshlrev_b32_e32 v84, 3, v172
	v_lshl_add_u64 v[82:83], s[4:5], 0, v[0:1]
	s_lshl_b64 s[4:5], s[0:1], 11
	s_add_u32 s8, s80, s4
	s_addc_u32 s9, s81, s5
	s_ashr_i32 s7, s6, 31
	s_lshl_b64 s[10:11], s[6:7], 11
	s_add_u32 s12, s44, s4
	v_mov_b32_e32 v85, v1
	s_addc_u32 s13, s45, s5
	v_lshlrev_b32_e32 v0, 4, v172
	s_cmpk_lt_i32 s0, 0x4000
	s_cbranch_scc0 .Ln3a_nopre
	v_lshl_add_u64 v[228:229], s[12:13], 0, v[84:85]
	global_load_dwordx2 v[220:221], v[228:229], off
	global_load_dwordx2 v[222:223], v[228:229], off offset:512
	global_load_dwordx2 v[224:225], v[228:229], off offset:1024
	global_load_dwordx2 v[226:227], v[228:229], off offset:1536
	s_waitcnt vmcnt(0)

; #define GAS __attribute__((address_space(1)))
; #define LAS __attribute__((address_space(3)))
; __device__ __forceinline__ unsigned pk2(float lo, float hi) { return f2bf(lo) | (f2bf(hi) << 16); }
; __device__ __forceinline__ unsigned pk4f8(float a, float b, float c, float d) { int w = 0; w = __builtin_amdgcn_cvt_pk_fp8_f32(a, b, w, false); w = __builtin_amdgcn_cvt_pk_fp8_f32(c, d, w, true); return (unsigned)w; }
;     ...
;         for (int j = 0; j < 4; ++j) s += (v[j].x * v[j].x + v[j].y * v[j].y) + (v[j].z * v[j].z + v[j].w * v[j].w);
;         const float rstd = 1.f / sqrtf(wave_sum(s, F.lane) * (1.f / DM) + NORM_EPS);
;         if (from_partials && m >= ML) { GAS f32x4* cr = (GAS f32x4*)((float*)(F.ws + WS_CTXRES) + (size_t)(m - ML) * DM) + F.lane;
; #pragma unroll
;             for (int j = 0; j < 4; ++j) cr[64 * j] = v[j]; }
;         GAS v2u* o8 = (GAS v2u*)(XN + (size_t)m * DM) + F.lane;
;         GAS unsigned* o4 = (GAS unsigned*)((unsigned char*)XN + (size_t)m * DM) + F.lane;
; #pragma unroll
;         for (int j = 0; j < 4; ++j) { const int col = 4 * F.lane + 256 * j;
;             const f32x4 g = *(const LAS f32x4*)(gl + col), sc = *(const LAS f32x4*)(scl + cnd * 1024 + col), sh = *(const LAS f32x4*)(shl + cnd * 1024 + col);
;             const f32x4 y = (v[j] * rstd) * g * sc + sh;
;             if (xn_fp8) o4[64 * j] = pk4f8(y.x, y.y, y.z, y.w);
;             else { v2u w; w.x = pk2(y.x, y.y); w.y = pk2(y.z, y.w); o8[64 * j] = w; } }
.LBB0_160:
	v_pk_mul_f32 v[38:39], v[32:33], v[32:33]
	v_pk_mul_f32 v[40:41], v[30:31], v[30:31]
	v_pk_mul_f32 v[34:35], v[28:29], v[28:29]
	v_pk_mul_f32 v[36:37], v[26:27], v[26:27]
	v_pk_mov_b32 v[42:43], v[40:41], v[38:39] op_sel:[1,0]
	v_mov_b32_e32 v41, v39
	v_pk_add_f32 v[38:39], v[42:43], v[40:41]
	v_pk_mov_b32 v[40:41], v[36:37], v[34:35] op_sel:[1,0]
	v_mov_b32_e32 v37, v35
	v_pk_add_f32 v[34:35], v[40:41], v[36:37]
	v_pk_add_f32 v[38:39], v[38:39], v[38:39] op_sel_hi:[0,1]
	v_pk_add_f32 v[34:35], v[34:35], v[34:35] op_sel_hi:[0,1]
	v_mul_f32_e32 v34, v22, v22
	v_pk_fma_f32 v[36:37], v[22:23], v[22:23], v[34:35] op_sel_hi:[1,1,0]
	v_mul_f32_e32 v34, v24, v24
	v_pk_fma_f32 v[40:41], v[24:25], v[24:25], v[34:35] op_sel_hi:[1,1,0]
	v_mul_f32_e32 v36, v18, v18
	v_mul_f32_e32 v40, v19, v19
	v_mul_f32_e32 v38, v20, v20
	v_mul_f32_e32 v34, v21, v21
	v_pk_add_f32 v[36:37], v[36:37], v[40:41]
	v_pk_add_f32 v[34:35], v[38:39], v[34:35]
	s_and_b64 s[4:5], exec, s[4:5]
	v_pk_add_f32 v[34:35], v[36:37], v[34:35]
	s_movk_i32 s1, 0x800
	v_add_f32_e32 v34, v34, v35
	s_cselect_b32 s1, 0x400, s1
	s_cmpk_gt_i32 s0, 0x1fff
	v_add_f32_dpp v34, v34, v34 row_ror:8 row_mask:0xf bank_mask:0xf bound_ctrl:1
	s_cselect_b32 s1, s1, 0
	v_lshl_add_u64 v[44:45], s[8:9], 0, v[84:85]
	v_add_f32_dpp v34, v34, v34 row_ror:4 row_mask:0xf bank_mask:0xf bound_ctrl:1
	s_add_i32 s0, s0, s6
	s_add_u32 s8, s8, s10
	v_add_f32_dpp v34, v34, v34 row_ror:2 row_mask:0xf bank_mask:0xf bound_ctrl:1
	s_addc_u32 s9, s9, s11
	s_add_u32 s12, s12, s10
	v_add_f32_dpp v34, v34, v34 row_ror:1 row_mask:0xf bank_mask:0xf bound_ctrl:1
	s_addc_u32 s13, s13, s11
	s_cmpk_lt_i32 s0, 0x4000
	s_cbranch_scc0 .Ln3a_nopf
	v_lshl_add_u64 v[228:229], s[12:13], 0, v[84:85]
	global_load_dwordx2 v[220:221], v[228:229], off
	global_load_dwordx2 v[222:223], v[228:229], off offset:512
	global_load_dwordx2 v[224:225], v[228:229], off offset:1024
	global_load_dwordx2 v[226:227], v[228:229], off offset:1536
.Ln3a_nopf:
	v_readlane_b32 s7, v34, 16
	v_readlane_b32 s14, v34, 48
	v_readlane_b32 s4, v34, 0
	v_readlane_b32 s5, v34, 32
	v_mov_b32_e32 v34, s7
	v_mov_b32_e32 v35, s14
	v_pk_add_f32 v[34:35], s[4:5], v[34:35]
	s_mov_b32 s4, 0xf800000
	v_add_f32_e32 v34, v34, v35
	v_fmamk_f32 v34, v34, 0x3a800000, v173
	v_cmp_gt_f32_e32 vcc, s4, v34
	v_mul_f32_e32 v35, 0x4f800000, v34
	s_cmpk_lt_i32 s0, 0x4200
	v_cndmask_b32_e32 v34, v34, v35, vcc
	v_sqrt_f32_e32 v35, v34
	s_nop 0
	v_add_u32_e32 v36, -1, v35
	v_fma_f32 v37, -v36, v35, v34
	v_cmp_ge_f32_e64 s[4:5], 0, v37
	v_add_u32_e32 v37, 1, v35
	s_nop 0
	v_cndmask_b32_e64 v36, v35, v36, s[4:5]
	v_fma_f32 v35, -v37, v35, v34
	v_cmp_lt_f32_e64 s[4:5], 0, v35
	s_nop 1
	v_cndmask_b32_e64 v35, v36, v37, s[4:5]
	v_mul_f32_e32 v36, 0x37800000, v35
	v_cndmask_b32_e32 v35, v35, v36, vcc
	v_cmp_class_f32_e32 vcc, v34, v186
	s_nop 1
	v_cndmask_b32_e32 v34, v35, v34, vcc
	v_div_scale_f32 v35, s[4:5], v34, v34, 1.0
	v_rcp_f32_e32 v36, v35
	s_movk_i32 s4, 0x7fff
	s_mov_b32 s5, 0x3300000
	v_fma_f32 v37, -v35, v36, 1.0
	v_fmac_f32_e32 v36, v37, v36
	v_div_scale_f32 v37, vcc, 1.0, v34, 1.0
	v_mul_f32_e32 v38, v37, v36
	v_fma_f32 v39, -v35, v38, v37
	v_fmac_f32_e32 v38, v39, v36
	v_fma_f32 v35, -v35, v38, v37
	v_div_fmas_f32 v35, v35, v36, v38
	v_div_fixup_f32 v34, v35, v34, 1.0
	v_lshl_add_u32 v35, s1, 2, v102
	ds_read_b128 v[36:39], v35 offset:4096
	ds_read_b128 v[40:43], v35 offset:16384
	v_pk_mul_f32 v[30:31], v[30:31], v[34:35] op_sel_hi:[1,0]
	v_pk_mul_f32 v[32:33], v[32:33], v[34:35] op_sel_hi:[1,0]
	s_waitcnt lgkmcnt(5)
	v_pk_mul_f32 v[30:31], v[2:3], v[30:31]
	v_pk_mul_f32 v[32:33], v[4:5], v[32:33]
	s_waitcnt lgkmcnt(0)
	v_pk_fma_f32 v[30:31], v[36:37], v[30:31], v[40:41]
	v_pk_fma_f32 v[32:33], v[38:39], v[32:33], v[42:43]
	v_bfe_u32 v36, v30, 16, 1
	v_add3_u32 v30, v30, v36, s4
	v_bfe_u32 v36, v31, 16, 1
	v_lshrrev_b32_e32 v30, 16, v30
	v_add3_u32 v31, v31, v36, s4
	s_mov_b32 s1, 0xffff0000
	v_and_or_b32 v36, v31, s1, v30
	v_bfe_u32 v30, v32, 16, 1
	v_add3_u32 v30, v32, v30, s4
	v_bfe_u32 v31, v33, 16, 1
	v_lshrrev_b32_e32 v30, 16, v30
	v_add3_u32 v31, v33, v31, s4
	v_and_or_b32 v37, v31, s1, v30
	v_add_co_u32_e32 v30, vcc, s5, v44
	v_pk_mul_f32 v[26:27], v[26:27], v[34:35] op_sel_hi:[1,0]
	s_nop 0
	v_addc_co_u32_e32 v31, vcc, 0, v45, vcc
	global_store_dwordx2 v[30:31], v[36:37], off
	ds_read_b128 v[36:39], v35 offset:5120
	ds_read_b128 v[40:43], v35 offset:17408
	v_pk_mul_f32 v[26:27], v[6:7], v[26:27]
	v_pk_mul_f32 v[28:29], v[28:29], v[34:35] op_sel_hi:[1,0]
	v_pk_mul_f32 v[22:23], v[22:23], v[34:35] op_sel_hi:[1,0]
	v_pk_mul_f32 v[28:29], v[8:9], v[28:29]
	s_waitcnt lgkmcnt(0)
	v_pk_fma_f32 v[26:27], v[36:37], v[26:27], v[40:41]
	v_pk_fma_f32 v[28:29], v[38:39], v[28:29], v[42:43]
	v_bfe_u32 v32, v26, 16, 1
	v_add3_u32 v26, v26, v32, s4
	v_bfe_u32 v32, v27, 16, 1
	v_lshrrev_b32_e32 v26, 16, v26
	v_add3_u32 v27, v27, v32, s4
	v_and_or_b32 v26, v27, s1, v26
	v_bfe_u32 v27, v28, 16, 1
	v_add3_u32 v27, v28, v27, s4
	v_bfe_u32 v28, v29, 16, 1
	v_lshrrev_b32_e32 v27, 16, v27
	v_add3_u32 v28, v29, v28, s4
	v_and_or_b32 v27, v28, s1, v27
	global_store_dwordx2 v[30:31], v[26:27], off offset:512
	ds_read_b128 v[26:29], v35 offset:6144
	ds_read_b128 v[36:39], v35 offset:18432
	v_pk_mul_f32 v[22:23], v[10:11], v[22:23]
	v_pk_mul_f32 v[24:25], v[24:25], v[34:35] op_sel_hi:[1,0]
	v_pk_mul_f32 v[18:19], v[18:19], v[34:35] op_sel_hi:[1,0]
	v_pk_mul_f32 v[24:25], v[12:13], v[24:25]
	s_waitcnt lgkmcnt(0)
	v_pk_fma_f32 v[22:23], v[26:27], v[22:23], v[36:37]
	v_pk_fma_f32 v[24:25], v[28:29], v[24:25], v[38:39]
	v_bfe_u32 v26, v22, 16, 1
	v_add3_u32 v22, v22, v26, s4
	v_bfe_u32 v26, v23, 16, 1
	v_lshrrev_b32_e32 v22, 16, v22
	v_add3_u32 v23, v23, v26, s4
	v_and_or_b32 v22, v23, s1, v22
	v_bfe_u32 v23, v24, 16, 1
	v_add3_u32 v23, v24, v23, s4
	v_bfe_u32 v24, v25, 16, 1
	v_lshrrev_b32_e32 v23, 16, v23
	v_add3_u32 v24, v25, v24, s4
	v_and_or_b32 v23, v24, s1, v23
	global_store_dwordx2 v[30:31], v[22:23], off offset:1024
	ds_read_b128 v[22:25], v35 offset:7168
	ds_read_b128 v[26:29], v35 offset:19456
	v_pk_mul_f32 v[18:19], v[18:19], v[14:15]
	v_pk_mul_f32 v[20:21], v[20:21], v[34:35] op_sel_hi:[1,0]
	s_waitcnt lgkmcnt(0)
	v_pk_fma_f32 v[18:19], v[18:19], v[22:23], v[26:27]
	s_nop 0
	v_bfe_u32 v22, v18, 16, 1
	v_pk_mul_f32 v[20:21], v[20:21], v[16:17]
	v_add3_u32 v18, v18, v22, s4
	v_bfe_u32 v22, v19, 16, 1
	v_pk_fma_f32 v[20:21], v[20:21], v[24:25], v[28:29]
	v_lshrrev_b32_e32 v18, 16, v18
	v_add3_u32 v19, v19, v22, s4
	v_and_or_b32 v18, v19, s1, v18
	v_bfe_u32 v19, v20, 16, 1
	v_add3_u32 v19, v20, v19, s4
	v_bfe_u32 v20, v21, 16, 1
	v_lshrrev_b32_e32 v19, 16, v19
	v_add3_u32 v20, v21, v20, s4
	v_and_or_b32 v19, v20, s1, v19
	global_store_dwordx2 v[30:31], v[18:19], off offset:1536
	s_cbranch_scc0 .LBB0_178

; #define GAS __attribute__((address_space(1)))
;     ...
;         if (lat_bf16 && m < ML) {
;             const GAS v2u* xb = (const GAS v2u*)((const bf16*)src_lat + (size_t)m * DM) + F.lane;
;             v2u w[4];
; #pragma unroll
;             for (int j = 0; j < 4; ++j) w[j] = xb[64 * j];
; #pragma unroll
;             for (int j = 0; j < 4; ++j) v[j] = f32x4{bflo(w[j].x), bfhi(w[j].x), bflo(w[j].y), bfhi(w[j].y)};
.LBB0_165:
	s_waitcnt vmcnt(4)
	v_lshlrev_b32_e32 v30, 16, v220
	v_and_b32_e32 v31, 0xffff0000, v220
	v_lshlrev_b32_e32 v32, 16, v221
	v_and_b32_e32 v33, 0xffff0000, v221
	v_lshlrev_b32_e32 v26, 16, v222
	v_and_b32_e32 v27, 0xffff0000, v222
	v_lshlrev_b32_e32 v28, 16, v223
	v_and_b32_e32 v29, 0xffff0000, v223
	v_lshlrev_b32_e32 v22, 16, v224
	v_and_b32_e32 v23, 0xffff0000, v224
	v_lshlrev_b32_e32 v24, 16, v225
	v_and_b32_e32 v25, 0xffff0000, v225
	v_lshlrev_b32_e32 v18, 16, v226
	v_and_b32_e32 v19, 0xffff0000, v226
	v_lshlrev_b32_e32 v20, 16, v227
	v_and_b32_e32 v21, 0xffff0000, v227
	s_cmpk_lt_i32 s0, 0x4000
	s_cbranch_scc1 .LBB0_160

;     ...
;     for (int i = F.tid; i < 1024; i += NWAVES * 64) {
;         gl[i] = gw_[i];
; #pragma unroll
;         for (int cnd = 0; cnd < 3; ++cnd) {
;             float sh, sc;
;             if (from_partials) { sh = ada_b[layer * 6144 + offsh + i]; sc = ada_b[layer * 6144 + offsc + i];
;                 float ph[ADA_KS], pc[ADA_KS];
; #pragma unroll
;                 for (int ks = 0; ks < ADA_KS; ++ks) { const float* p = modp + ((size_t)(ks * 2 + layer) * 3 + cnd) * 6144; ph[ks] = p[offsh + i]; pc[ks] = p[offsc + i]; }
; #pragma unroll
;                 for (int ks = 0; ks < ADA_KS; ++ks) { sh += ph[ks]; sc += pc[ks]; } }
;             else { sh = mod[(layer * 3 + cnd) * 6144 + offsh + i]; sc = mod[(layer * 3 + cnd) * 6144 + offsc + i]; }
;             scl[cnd * 1024 + i] = 1.f + sc; shl[cnd * 1024 + i] = sh;
;         }
;     }
.LBB0_187:
	v_lshlrev_b32_e32 v220, 2, v2
	v_lshlrev_b32_e32 v221, 2, v3
	global_load_dword v236, v220, s[0:1]
	global_load_dword v237, v221, s[0:1]
	v_add_u32_e32 v222, s14, v220
	v_add_u32_e32 v223, s14, v221
	global_load_dword v228, v222, s[10:11] offset:-4096
	global_load_dword v229, v223, s[10:11] offset:-4096
	global_load_dword v230, v222, s[10:11]
	global_load_dword v231, v223, s[10:11]
	v_add_u32_e32 v222, s15, v220
	v_add_u32_e32 v223, s15, v221
	global_load_dword v232, v222, s[10:11] offset:-4096
	global_load_dword v233, v223, s[10:11] offset:-4096
	global_load_dword v234, v222, s[10:11]
	global_load_dword v235, v223, s[10:11]
	v_add_u32_e32 v222, s16, v220
	v_add_u32_e32 v223, s16, v221
	global_load_dword v238, v222, s[10:11] offset:-4096
	global_load_dword v239, v223, s[10:11] offset:-4096
	global_load_dword v240, v222, s[10:11]
	global_load_dword v241, v223, s[10:11]
	v_add_u32_e32 v5, -2, v5
	v_add_u32_e32 v224, 0x400, v2
	v_add_u32_e32 v225, 0x400, v3
	v_lshl_add_u32 v226, v224, 2, 0
	v_lshl_add_u32 v227, v225, 2, 0
	v_cmp_eq_u32_e32 vcc, 0, v5
	s_or_b64 s[12:13], vcc, s[12:13]
	s_waitcnt vmcnt(0)
	ds_write2st64_b32 v6, v236, v237 offset1:8
	v_add_f32_e32 v230, 1.0, v230
	v_add_f32_e32 v231, 1.0, v231
	ds_write2st64_b32 v6, v230, v231 offset0:16 offset1:24
	ds_write2st64_b32 v6, v228, v229 offset0:64 offset1:72
	v_add_f32_e32 v234, 1.0, v234
	v_add_f32_e32 v235, 1.0, v235
	ds_write_b32 v226, v234 offset:4096
	ds_write_b32 v227, v235 offset:4096
	ds_write_b32 v226, v232 offset:16384
	ds_write_b32 v227, v233 offset:16384
	v_add_f32_e32 v240, 1.0, v240
	v_add_f32_e32 v241, 1.0, v241
	ds_write_b32 v220, v240 offset:12288
	ds_write_b32 v221, v241 offset:12288
	ds_write_b32 v220, v238 offset:24576
	ds_write_b32 v221, v239 offset:24576
	v_add_u32_e32 v6, 0x1000, v6
	v_mov_b32_e32 v2, v224
	v_mov_b32_e32 v3, v225
	s_andn2_b64 exec, exec, s[12:13]
	s_cbranch_execnz .LBB0_187
	s_nop 0
	s_nop 0
	s_nop 0
	s_nop 0
	s_nop 0
	s_nop 0
	s_nop 0
	s_nop 0
	s_nop 0
	s_nop 0
	s_nop 0
	s_nop 0
	s_nop 0
	s_nop 0
	s_nop 0
	s_nop 0
	s_nop 0
	s_nop 0
	s_nop 0
	s_nop 0
	s_nop 0
	s_nop 0
	s_nop 0
	s_nop 0
	s_nop 0
	s_nop 0
	s_nop 0
	s_nop 0
	s_nop 0
	s_nop 0
	s_nop 0
	s_nop 0
	s_nop 0
	s_or_b64 exec, exec, s[12:13]
	v_cmp_ne_u32_e32 vcc, v0, v4
	v_lshl_add_u32 v2, v4, 9, v170
	s_orn2_b64 s[10:11], vcc, exec

; #define GAS __attribute__((address_space(1)))
;     ...
;     bf16* XN = (bf16*)(F.ws + WS_XN);
;     const int gw = F.vcu * NWAVES + F.wave, NGW = F.G * NWAVES;
;     for (int m = gw; m < nrows; m += NGW) {
;         const float* xrow = m < ML ? src_lat + (size_t)m * DM : src_ctx + (size_t)(m - ML) * DM;
;         const int cnd = m < SEQ ? 0 : (m < ML ? 1 : 2);
;         const GAS f32x4* xr = (const GAS f32x4*)xrow + F.lane;
;         f32x4 v[4]; float s = 0.f;
;         if (lat_bf16 && m < ML) {
;             const GAS v2u* xb = (const GAS v2u*)((const bf16*)src_lat + (size_t)m * DM) + F.lane;
;             v2u w[4];
; #pragma unroll
;             for (int j = 0; j < 4; ++j) w[j] = xb[64 * j];
; #pragma unroll
;             for (int j = 0; j < 4; ++j) v[j] = f32x4{bflo(w[j].x), bfhi(w[j].x), bflo(w[j].y), bfhi(w[j].y)};
.LBB0_192:
	s_or_b64 exec, exec, s[4:5]
	v_readlane_b32 s0, v243, 20
	s_lshl_b32 s0, s0, 3
	v_readlane_b32 s1, v243, 24
	s_add_i32 s0, s0, s1
	s_cmpk_gt_i32 s0, 0x41ff
	s_waitcnt lgkmcnt(0)
	s_barrier
	s_cbranch_scc1 .LBB0_201
	v_lshlrev_b32_e32 v0, 4, v172
	v_readlane_b32 s4, v243, 22
	v_readlane_b32 s1, v243, 18
	v_add_u32_e32 v39, 0, v0
	v_readlane_b32 s5, v243, 23
	s_lshl_b32 s8, s1, 3
	s_waitcnt vmcnt(0)
	ds_read_b128 v[2:5], v39
	ds_read_b128 v[6:9], v39 offset:1024
	ds_read_b128 v[10:13], v39 offset:2048
	ds_read_b128 v[14:17], v39 offset:3072
	v_lshl_add_u64 v[34:35], s[4:5], 0, v[0:1]
	v_lshl_add_u64 v[18:19], s[80:81], 0, v[0:1]
	s_mov_b64 s[4:5], 0x5400000
	s_ashr_i32 s1, s0, 31
	v_lshl_add_u64 v[36:37], v[18:19], 0, s[4:5]
	s_lshl_b64 s[4:5], s[0:1], 11
	s_add_u32 s10, s80, s4
	s_addc_u32 s11, s81, s5
	s_ashr_i32 s9, s8, 31
	s_lshl_b64 s[12:13], s[8:9], 11
	s_add_u32 s14, s44, s4
	v_lshlrev_b32_e32 v0, 3, v172
	s_addc_u32 s15, s45, s5
	s_cmpk_lt_i32 s0, 0x4000
	s_cbranch_scc0 .Ln3b_nopre
	v_lshl_add_u64 v[228:229], s[14:15], 0, v[0:1]
	global_load_dwordx2 v[220:221], v[228:229], off
	global_load_dwordx2 v[222:223], v[228:229], off offset:512
	global_load_dwordx2 v[224:225], v[228:229], off offset:1024
	global_load_dwordx2 v[226:227], v[228:229], off offset:1536
	s_waitcnt vmcnt(0)

; #define GAS __attribute__((address_space(1)))
; #define LAS __attribute__((address_space(3)))
; __device__ __forceinline__ unsigned pk2(float lo, float hi) { return f2bf(lo) | (f2bf(hi) << 16); }
; __device__ __forceinline__ unsigned pk4f8(float a, float b, float c, float d) { int w = 0; w = __builtin_amdgcn_cvt_pk_fp8_f32(a, b, w, false); w = __builtin_amdgcn_cvt_pk_fp8_f32(c, d, w, true); return (unsigned)w; }
;     ...
;         for (int j = 0; j < 4; ++j) s += (v[j].x * v[j].x + v[j].y * v[j].y) + (v[j].z * v[j].z + v[j].w * v[j].w);
;         const float rstd = 1.f / sqrtf(wave_sum(s, F.lane) * (1.f / DM) + NORM_EPS);
;         if (from_partials && m >= ML) { GAS f32x4* cr = (GAS f32x4*)((float*)(F.ws + WS_CTXRES) + (size_t)(m - ML) * DM) + F.lane;
; #pragma unroll
;             for (int j = 0; j < 4; ++j) cr[64 * j] = v[j]; }
;         GAS v2u* o8 = (GAS v2u*)(XN + (size_t)m * DM) + F.lane;
;         GAS unsigned* o4 = (GAS unsigned*)((unsigned char*)XN + (size_t)m * DM) + F.lane;
; #pragma unroll
;         for (int j = 0; j < 4; ++j) { const int col = 4 * F.lane + 256 * j;
;             const f32x4 g = *(const LAS f32x4*)(gl + col), sc = *(const LAS f32x4*)(scl + cnd * 1024 + col), sh = *(const LAS f32x4*)(shl + cnd * 1024 + col);
;             const f32x4 y = (v[j] * rstd) * g * sc + sh;
;             if (xn_fp8) o4[64 * j] = pk4f8(y.x, y.y, y.z, y.w);
;             else { v2u w; w.x = pk2(y.x, y.y); w.y = pk2(y.z, y.w); o8[64 * j] = w; } }
.LBB0_194:
	v_pk_mul_f32 v[44:45], v[32:33], v[32:33]
	v_pk_mul_f32 v[46:47], v[30:31], v[30:31]
	v_pk_mul_f32 v[40:41], v[28:29], v[28:29]
	v_pk_mul_f32 v[42:43], v[26:27], v[26:27]
	v_pk_mov_b32 v[48:49], v[46:47], v[44:45] op_sel:[1,0]
	v_mov_b32_e32 v47, v45
	v_pk_add_f32 v[44:45], v[48:49], v[46:47]
	v_pk_mov_b32 v[46:47], v[42:43], v[40:41] op_sel:[1,0]
	v_mov_b32_e32 v43, v41
	v_mul_f32_e32 v38, v22, v22
	v_pk_add_f32 v[40:41], v[46:47], v[42:43]
	v_pk_fma_f32 v[42:43], v[22:23], v[22:23], v[38:39] op_sel_hi:[1,1,0]
	v_mul_f32_e32 v38, v24, v24
	v_pk_add_f32 v[44:45], v[44:45], v[44:45] op_sel_hi:[0,1]
	v_pk_add_f32 v[40:41], v[40:41], v[40:41] op_sel_hi:[0,1]
	v_pk_fma_f32 v[46:47], v[24:25], v[24:25], v[38:39] op_sel_hi:[1,1,0]
	v_mul_f32_e32 v42, v18, v18
	v_mul_f32_e32 v46, v19, v19
	v_mul_f32_e32 v44, v20, v20
	v_mul_f32_e32 v40, v21, v21
	v_pk_add_f32 v[42:43], v[42:43], v[46:47]
	v_pk_add_f32 v[40:41], v[44:45], v[40:41]
	s_and_b64 s[4:5], exec, s[4:5]
	v_pk_add_f32 v[40:41], v[42:43], v[40:41]
	s_movk_i32 s1, 0x800
	v_add_f32_e32 v38, v40, v41
	s_cselect_b32 s1, 0x400, s1
	s_cmpk_gt_i32 s0, 0x1fff
	v_add_f32_dpp v38, v38, v38 row_ror:8 row_mask:0xf bank_mask:0xf bound_ctrl:1
	s_cselect_b32 s1, s1, 0
	v_lshl_add_u32 v50, s1, 2, v39
	v_add_f32_dpp v38, v38, v38 row_ror:4 row_mask:0xf bank_mask:0xf bound_ctrl:1
	s_mov_b32 s1, 0xffff0000
	v_lshl_add_u64 v[48:49], s[10:11], 0, v[0:1]
	v_add_f32_dpp v38, v38, v38 row_ror:2 row_mask:0xf bank_mask:0xf bound_ctrl:1
	s_add_i32 s0, s0, s8
	s_add_u32 s10, s10, s12
	v_add_f32_dpp v38, v38, v38 row_ror:1 row_mask:0xf bank_mask:0xf bound_ctrl:1
	s_addc_u32 s11, s11, s13
	v_readlane_b32 s9, v38, 16
	v_readlane_b32 s16, v38, 48
	v_readlane_b32 s4, v38, 0
	v_readlane_b32 s5, v38, 32
	v_mov_b32_e32 v40, s9
	v_mov_b32_e32 v41, s16
	v_pk_add_f32 v[40:41], s[4:5], v[40:41]
	s_mov_b32 s4, 0xf800000
	v_add_f32_e32 v38, v40, v41
	v_fmamk_f32 v38, v38, 0x3a800000, v173
	v_cmp_gt_f32_e32 vcc, s4, v38
	v_mul_f32_e32 v40, 0x4f800000, v38
	s_add_u32 s14, s14, s12
	v_cndmask_b32_e32 v38, v38, v40, vcc
	v_sqrt_f32_e32 v40, v38
	s_addc_u32 s15, s15, s13
	s_cmpk_lt_i32 s0, 0x4000
	s_cbranch_scc0 .Ln3b_nopf
	v_lshl_add_u64 v[228:229], s[14:15], 0, v[0:1]
	global_load_dwordx2 v[220:221], v[228:229], off
	global_load_dwordx2 v[222:223], v[228:229], off offset:512
	global_load_dwordx2 v[224:225], v[228:229], off offset:1024
	global_load_dwordx2 v[226:227], v[228:229], off offset:1536
.Ln3b_nopf:
	s_cmpk_lt_i32 s0, 0x4200
	v_add_u32_e32 v41, -1, v40
	v_fma_f32 v42, -v41, v40, v38
	v_cmp_ge_f32_e64 s[4:5], 0, v42
	v_add_u32_e32 v42, 1, v40
	s_nop 0
	v_cndmask_b32_e64 v41, v40, v41, s[4:5]
	v_fma_f32 v40, -v42, v40, v38
	v_cmp_lt_f32_e64 s[4:5], 0, v40
	s_nop 1
	v_cndmask_b32_e64 v40, v41, v42, s[4:5]
	v_mul_f32_e32 v41, 0x37800000, v40
	v_cndmask_b32_e32 v40, v40, v41, vcc
	v_cmp_class_f32_e32 vcc, v38, v186
	s_nop 1
	v_cndmask_b32_e32 v38, v40, v38, vcc
	v_div_scale_f32 v40, s[4:5], v38, v38, 1.0
	v_rcp_f32_e32 v41, v40
	s_movk_i32 s4, 0x7fff
	s_mov_b32 s5, 0x3300000
	v_fma_f32 v42, -v40, v41, 1.0
	v_fmac_f32_e32 v41, v42, v41
	v_div_scale_f32 v42, vcc, 1.0, v38, 1.0
	v_mul_f32_e32 v43, v42, v41
	v_fma_f32 v44, -v40, v43, v42
	v_fmac_f32_e32 v43, v44, v41
	v_fma_f32 v40, -v40, v43, v42
	v_div_fmas_f32 v40, v40, v41, v43
	v_div_fixup_f32 v38, v40, v38, 1.0
	ds_read_b128 v[40:43], v50 offset:4096
	ds_read_b128 v[44:47], v50 offset:16384
	v_pk_mul_f32 v[30:31], v[30:31], v[38:39] op_sel_hi:[1,0]
	v_pk_mul_f32 v[32:33], v[32:33], v[38:39] op_sel_hi:[1,0]
	s_waitcnt lgkmcnt(5)
	v_pk_mul_f32 v[30:31], v[2:3], v[30:31]
	v_pk_mul_f32 v[32:33], v[4:5], v[32:33]
	s_waitcnt lgkmcnt(0)
	v_pk_fma_f32 v[30:31], v[40:41], v[30:31], v[44:45]
	v_pk_fma_f32 v[32:33], v[42:43], v[32:33], v[46:47]
	v_bfe_u32 v40, v30, 16, 1
	v_add3_u32 v30, v30, v40, s4
	v_bfe_u32 v40, v31, 16, 1
	v_lshrrev_b32_e32 v30, 16, v30
	v_add3_u32 v31, v31, v40, s4
	v_and_or_b32 v40, v31, s1, v30
	v_bfe_u32 v30, v32, 16, 1
	v_add3_u32 v30, v32, v30, s4
	v_bfe_u32 v31, v33, 16, 1
	v_lshrrev_b32_e32 v30, 16, v30
	v_add3_u32 v31, v33, v31, s4
	v_and_or_b32 v41, v31, s1, v30
	v_add_co_u32_e32 v30, vcc, s5, v48
	v_pk_mul_f32 v[26:27], v[26:27], v[38:39] op_sel_hi:[1,0]
	s_nop 0
	v_addc_co_u32_e32 v31, vcc, 0, v49, vcc
	global_store_dwordx2 v[30:31], v[40:41], off
	ds_read_b128 v[40:43], v50 offset:5120
	ds_read_b128 v[44:47], v50 offset:17408
	v_pk_mul_f32 v[26:27], v[6:7], v[26:27]
	v_pk_mul_f32 v[28:29], v[28:29], v[38:39] op_sel_hi:[1,0]
	v_pk_mul_f32 v[22:23], v[22:23], v[38:39] op_sel_hi:[1,0]
	v_pk_mul_f32 v[28:29], v[8:9], v[28:29]
	s_waitcnt lgkmcnt(0)
	v_pk_fma_f32 v[26:27], v[40:41], v[26:27], v[44:45]
	v_pk_fma_f32 v[28:29], v[42:43], v[28:29], v[46:47]
	v_bfe_u32 v32, v26, 16, 1
	v_add3_u32 v26, v26, v32, s4
	v_bfe_u32 v32, v27, 16, 1
	v_lshrrev_b32_e32 v26, 16, v26
	v_add3_u32 v27, v27, v32, s4
	v_and_or_b32 v26, v27, s1, v26
	v_bfe_u32 v27, v28, 16, 1
	v_add3_u32 v27, v28, v27, s4
	v_bfe_u32 v28, v29, 16, 1
	v_lshrrev_b32_e32 v27, 16, v27
	v_add3_u32 v28, v29, v28, s4
	v_and_or_b32 v27, v28, s1, v27
	global_store_dwordx2 v[30:31], v[26:27], off offset:512
	ds_read_b128 v[26:29], v50 offset:6144
	ds_read_b128 v[40:43], v50 offset:18432
	v_pk_mul_f32 v[22:23], v[10:11], v[22:23]
	v_pk_mul_f32 v[24:25], v[24:25], v[38:39] op_sel_hi:[1,0]
	v_pk_mul_f32 v[18:19], v[18:19], v[38:39] op_sel_hi:[1,0]
	v_pk_mul_f32 v[24:25], v[12:13], v[24:25]
	s_waitcnt lgkmcnt(0)
	v_pk_fma_f32 v[22:23], v[26:27], v[22:23], v[40:41]
	v_pk_fma_f32 v[24:25], v[28:29], v[24:25], v[42:43]
	v_bfe_u32 v26, v22, 16, 1
	v_add3_u32 v22, v22, v26, s4
	v_bfe_u32 v26, v23, 16, 1
	v_lshrrev_b32_e32 v22, 16, v22
	v_add3_u32 v23, v23, v26, s4
	v_and_or_b32 v22, v23, s1, v22
	v_bfe_u32 v23, v24, 16, 1
	v_add3_u32 v23, v24, v23, s4
	v_bfe_u32 v24, v25, 16, 1
	v_lshrrev_b32_e32 v23, 16, v23
	v_add3_u32 v24, v25, v24, s4
	v_and_or_b32 v23, v24, s1, v23
	global_store_dwordx2 v[30:31], v[22:23], off offset:1024
	ds_read_b128 v[22:25], v50 offset:7168
	ds_read_b128 v[26:29], v50 offset:19456
	v_pk_mul_f32 v[18:19], v[18:19], v[14:15]
	v_pk_mul_f32 v[20:21], v[20:21], v[38:39] op_sel_hi:[1,0]
	s_waitcnt lgkmcnt(0)
	v_pk_fma_f32 v[18:19], v[18:19], v[22:23], v[26:27]
	s_nop 0
	v_bfe_u32 v22, v18, 16, 1
	v_pk_mul_f32 v[20:21], v[20:21], v[16:17]
	v_add3_u32 v18, v18, v22, s4
	v_bfe_u32 v22, v19, 16, 1
	v_pk_fma_f32 v[20:21], v[20:21], v[24:25], v[28:29]
	v_lshrrev_b32_e32 v18, 16, v18
	v_add3_u32 v19, v19, v22, s4
	v_and_or_b32 v18, v19, s1, v18
	v_bfe_u32 v19, v20, 16, 1
	v_add3_u32 v19, v20, v19, s4
	v_bfe_u32 v20, v21, 16, 1
	v_lshrrev_b32_e32 v19, 16, v19
	v_add3_u32 v20, v21, v20, s4
	v_and_or_b32 v19, v20, s1, v19
	global_store_dwordx2 v[30:31], v[18:19], off offset:1536
	s_cbranch_scc0 .LBB0_201
